# P6 k-loop: same SGPR-base LDS-DMA + pipelined LDS operand reads as P2/P8/P10
# speedup vs baseline: 1.0265x; 1.0000x over previous
.LBB0_944:
	s_ashr_i32 s29, s28, 31
	v_cmp_lt_i64_e32 vcc, s[30:31], v[154:155]
	s_lshl_b64 s[30:31], s[28:29], 20
	s_add_u32 s30, s48, s30
	s_addc_u32 s31, s49, s31
	s_and_b64 s[34:35], vcc, exec
	s_cselect_b32 s29, s31, s39
	s_cselect_b32 s63, s30, s38
	s_ashr_i32 s27, s26, 31
	s_lshl_b64 s[34:35], s[26:27], 20
	s_add_u32 s34, s54, s34
	s_addc_u32 s35, s55, s35
	s_and_b64 s[42:43], vcc, exec
	s_cselect_b32 s27, s35, s41
	s_cselect_b32 s64, s34, s40
	s_add_u32 s38, s38, 0x80080
	s_addc_u32 s39, s39, 0
	s_add_u32 s65, s40, 0x100
	s_addc_u32 s66, s41, 0
	s_mov_b32 s67, -2
	v_add_u32_e32 v158, 0x18000, v164
	v_add_u32_e32 v159, 0x1c000, v164
	ds_read_b128 v[130:133], v167
	ds_read_b128 v[134:137], v167 offset:1024
	ds_read_b128 v[138:141], v167 offset:2048
	ds_read_b128 v[142:145], v167 offset:3072
	ds_read_b128 v[172:175], v170
	ds_read_b128 v[176:179], v170 offset:1024
	ds_read_b128 v[180:183], v170 offset:2048
	ds_read_b128 v[184:187], v170 offset:3072
	ds_read_b128 v[188:191], v170 offset:4096
	ds_read_b128 v[192:195], v170 offset:5120
	ds_read_b128 v[196:199], v170 offset:6144
	ds_read_b128 v[200:203], v170 offset:7168
	s_add_u32 s40, s38, 0xfff80080
	s_addc_u32 s41, s39, -1
	s_cmp_eq_u32 s67, 28
	s_cselect_b32 s43, s29, s41
	s_cselect_b32 s42, s63, s40
	s_cselect_b32 s41, s27, s66
	s_cselect_b32 s40, s64, s65
	s_add_i32 m0, s37, 0xc000
	s_nop 0
	global_load_lds_dwordx4 v150, s[38:39]
	s_add_i32 m0, s37, 0xe000
	s_nop 0
	global_load_lds_dwordx4 v152, s[38:39]
	s_waitcnt vmcnt(10)
	s_barrier
	s_waitcnt lgkmcnt(0)
	s_setprio 1
	v_mfma_f32_16x16x32_bf16 v[126:129], v[130:133], v[172:175], 0
	ds_read_b128 v[204:207], v171
	v_mfma_f32_16x16x32_bf16 v[122:125], v[138:141], v[172:175], 0
	v_mfma_f32_16x16x32_bf16 v[114:117], v[130:133], v[180:183], 0
	v_mfma_f32_16x16x32_bf16 v[106:109], v[138:141], v[180:183], 0
	v_mfma_f32_16x16x32_bf16 v[98:101], v[130:133], v[188:191], 0
	ds_read_b128 v[208:211], v171 offset:1024
	v_mfma_f32_16x16x32_bf16 v[90:93], v[138:141], v[188:191], 0
	v_mfma_f32_16x16x32_bf16 v[82:85], v[130:133], v[196:199], 0
	v_mfma_f32_16x16x32_bf16 v[74:77], v[138:141], v[196:199], 0
	v_mfma_f32_16x16x32_bf16 v[126:129], v[134:137], v[176:179], v[126:129]
	ds_read_b128 v[212:215], v171 offset:2048
	v_mfma_f32_16x16x32_bf16 v[122:125], v[142:145], v[176:179], v[122:125]
	v_mfma_f32_16x16x32_bf16 v[114:117], v[134:137], v[184:187], v[114:117]
	v_mfma_f32_16x16x32_bf16 v[106:109], v[142:145], v[184:187], v[106:109]
	v_mfma_f32_16x16x32_bf16 v[98:101], v[134:137], v[192:195], v[98:101]
	ds_read_b128 v[216:219], v171 offset:3072
	v_mfma_f32_16x16x32_bf16 v[90:93], v[142:145], v[192:195], v[90:93]
	v_mfma_f32_16x16x32_bf16 v[82:85], v[134:137], v[200:203], v[82:85]
	v_mfma_f32_16x16x32_bf16 v[74:77], v[142:145], v[200:203], v[74:77]
	s_setprio 0
	s_barrier
	s_add_i32 s68, s59, s47
	s_add_u32 s96, s40, 0x80
	s_addc_u32 s97, s41, 0
	s_mov_b32 m0, s68
	s_nop 0
	global_load_lds_dwordx4 v146, s[40:41]
	s_add_i32 m0, s68, 0x2000
	s_nop 0
	global_load_lds_dwordx4 v148, s[40:41]
	s_waitcnt vmcnt(10)
	s_barrier
	s_waitcnt lgkmcnt(0)
	s_setprio 1
	v_mfma_f32_16x16x32_bf16 v[118:121], v[204:207], v[172:175], 0
	ds_read_b128 v[224:227], v170 offset:16384
	v_mfma_f32_16x16x32_bf16 v[110:113], v[212:215], v[172:175], 0
	v_mfma_f32_16x16x32_bf16 v[102:105], v[204:207], v[180:183], 0
	ds_read_b128 v[228:231], v170 offset:17408
	v_mfma_f32_16x16x32_bf16 v[94:97], v[212:215], v[180:183], 0
	v_mfma_f32_16x16x32_bf16 v[86:89], v[204:207], v[188:191], 0
	ds_read_b128 v[232:235], v170 offset:18432
	v_mfma_f32_16x16x32_bf16 v[78:81], v[212:215], v[188:191], 0
	v_mfma_f32_16x16x32_bf16 v[70:73], v[204:207], v[196:199], 0
	ds_read_b128 v[236:239], v170 offset:19456
	v_mfma_f32_16x16x32_bf16 v[66:69], v[212:215], v[196:199], 0
	v_mfma_f32_16x16x32_bf16 v[118:121], v[208:211], v[176:179], v[118:121]
	ds_read_b128 v[240:243], v170 offset:20480
	v_mfma_f32_16x16x32_bf16 v[110:113], v[216:219], v[176:179], v[110:113]
	v_mfma_f32_16x16x32_bf16 v[102:105], v[208:211], v[184:187], v[102:105]
	ds_read_b128 v[244:247], v170 offset:21504
	v_mfma_f32_16x16x32_bf16 v[94:97], v[216:219], v[184:187], v[94:97]
	v_mfma_f32_16x16x32_bf16 v[86:89], v[208:211], v[192:195], v[86:89]
	ds_read_b128 v[248:251], v170 offset:22528
	v_mfma_f32_16x16x32_bf16 v[78:81], v[216:219], v[192:195], v[78:81]
	v_mfma_f32_16x16x32_bf16 v[70:73], v[208:211], v[200:203], v[70:73]
	ds_read_b128 v[220:223], v170 offset:23552
	v_mfma_f32_16x16x32_bf16 v[66:69], v[216:219], v[200:203], v[66:69]
	s_setprio 0
	s_barrier
	s_mov_b32 m0, s37
	s_add_u32 s94, s42, 0x80
	s_addc_u32 s95, s43, 0
	global_load_lds_dwordx4 v146, s[42:43]
	s_mov_b32 m0, s50
	s_nop 0
	global_load_lds_dwordx4 v148, s[42:43]
	s_waitcnt vmcnt(8)
	s_barrier
	s_waitcnt lgkmcnt(0)
	s_setprio 1
	v_mfma_f32_16x16x32_bf16 v[62:65], v[130:133], v[224:227], 0
	ds_read_b128 v[172:175], v170 offset:32768
	v_mfma_f32_16x16x32_bf16 v[58:61], v[138:141], v[224:227], 0
	v_mfma_f32_16x16x32_bf16 v[54:57], v[130:133], v[232:235], 0
	ds_read_b128 v[176:179], v170 offset:33792
	v_mfma_f32_16x16x32_bf16 v[46:49], v[138:141], v[232:235], 0
	v_mfma_f32_16x16x32_bf16 v[38:41], v[130:133], v[240:243], 0
	ds_read_b128 v[180:183], v170 offset:34816
	v_mfma_f32_16x16x32_bf16 v[30:33], v[138:141], v[240:243], 0
	v_mfma_f32_16x16x32_bf16 v[22:25], v[130:133], v[248:251], 0
	ds_read_b128 v[184:187], v170 offset:35840
	v_mfma_f32_16x16x32_bf16 v[14:17], v[138:141], v[248:251], 0
	v_mfma_f32_16x16x32_bf16 v[62:65], v[134:137], v[228:231], v[62:65]
	ds_read_b128 v[188:191], v170 offset:36864
	v_mfma_f32_16x16x32_bf16 v[58:61], v[142:145], v[228:231], v[58:61]
	v_mfma_f32_16x16x32_bf16 v[54:57], v[134:137], v[236:239], v[54:57]
	ds_read_b128 v[192:195], v170 offset:37888
	v_mfma_f32_16x16x32_bf16 v[46:49], v[142:145], v[236:239], v[46:49]
	v_mfma_f32_16x16x32_bf16 v[38:41], v[134:137], v[244:247], v[38:41]
	ds_read_b128 v[196:199], v170 offset:38912
	v_mfma_f32_16x16x32_bf16 v[30:33], v[142:145], v[244:247], v[30:33]
	v_mfma_f32_16x16x32_bf16 v[22:25], v[134:137], v[220:223], v[22:25]
	ds_read_b128 v[200:203], v170 offset:39936
	v_mfma_f32_16x16x32_bf16 v[14:17], v[142:145], v[220:223], v[14:17]
	s_setprio 0
	s_barrier
	s_add_u32 s68, s40, 0x80000
	s_addc_u32 s69, s41, 0
	s_add_i32 s70, s60, s47
	s_mov_b32 m0, s70
	s_nop 0
	global_load_lds_dwordx4 v146, s[68:69]
	s_add_i32 m0, s70, 0x2000
	s_nop 0
	global_load_lds_dwordx4 v148, s[68:69]
	s_waitcnt vmcnt(10)
	s_barrier
	s_waitcnt lgkmcnt(0)
	s_setprio 1
	v_mfma_f32_16x16x32_bf16 v[50:53], v[204:207], v[224:227], 0
	ds_read_b128 v[130:133], v158
	v_mfma_f32_16x16x32_bf16 v[42:45], v[212:215], v[224:227], 0
	v_mfma_f32_16x16x32_bf16 v[34:37], v[204:207], v[232:235], 0
	v_mfma_f32_16x16x32_bf16 v[26:29], v[212:215], v[232:235], 0
	v_mfma_f32_16x16x32_bf16 v[18:21], v[204:207], v[240:243], 0
	ds_read_b128 v[134:137], v158 offset:1024
	v_mfma_f32_16x16x32_bf16 v[10:13], v[212:215], v[240:243], 0
	v_mfma_f32_16x16x32_bf16 v[6:9], v[204:207], v[248:251], 0
	v_mfma_f32_16x16x32_bf16 v[2:5], v[212:215], v[248:251], 0
	v_mfma_f32_16x16x32_bf16 v[50:53], v[208:211], v[228:231], v[50:53]
	ds_read_b128 v[138:141], v158 offset:2048
	v_mfma_f32_16x16x32_bf16 v[42:45], v[216:219], v[228:231], v[42:45]
	v_mfma_f32_16x16x32_bf16 v[34:37], v[208:211], v[236:239], v[34:37]
	v_mfma_f32_16x16x32_bf16 v[26:29], v[216:219], v[236:239], v[26:29]
	v_mfma_f32_16x16x32_bf16 v[18:21], v[208:211], v[244:247], v[18:21]
	ds_read_b128 v[142:145], v158 offset:3072
	v_mfma_f32_16x16x32_bf16 v[10:13], v[216:219], v[244:247], v[10:13]
	v_mfma_f32_16x16x32_bf16 v[6:9], v[208:211], v[220:223], v[6:9]
	v_mfma_f32_16x16x32_bf16 v[2:5], v[216:219], v[220:223], v[2:5]
	s_setprio 0
	s_barrier
	s_add_i32 s70, 0, 0x18000
	s_add_u32 s42, s42, 0x80000
	s_addc_u32 s43, s43, 0
	s_mov_b32 m0, s51
	s_nop 0
	global_load_lds_dwordx4 v146, s[42:43]
	s_mov_b32 m0, s52
	s_nop 0
	global_load_lds_dwordx4 v148, s[42:43]
	s_waitcnt vmcnt(10)
	s_barrier
	s_waitcnt lgkmcnt(0)
	s_setprio 1
	v_mfma_f32_16x16x32_bf16 v[126:129], v[130:133], v[172:175], v[126:129]
	ds_read_b128 v[204:207], v159
	v_mfma_f32_16x16x32_bf16 v[122:125], v[138:141], v[172:175], v[122:125]
	v_mfma_f32_16x16x32_bf16 v[114:117], v[130:133], v[180:183], v[114:117]
	v_mfma_f32_16x16x32_bf16 v[106:109], v[138:141], v[180:183], v[106:109]
	v_mfma_f32_16x16x32_bf16 v[98:101], v[130:133], v[188:191], v[98:101]
	ds_read_b128 v[208:211], v159 offset:1024
	v_mfma_f32_16x16x32_bf16 v[90:93], v[138:141], v[188:191], v[90:93]
	v_mfma_f32_16x16x32_bf16 v[82:85], v[130:133], v[196:199], v[82:85]
	v_mfma_f32_16x16x32_bf16 v[74:77], v[138:141], v[196:199], v[74:77]
	v_mfma_f32_16x16x32_bf16 v[126:129], v[134:137], v[176:179], v[126:129]
	ds_read_b128 v[212:215], v159 offset:2048
	v_mfma_f32_16x16x32_bf16 v[122:125], v[142:145], v[176:179], v[122:125]
	v_mfma_f32_16x16x32_bf16 v[114:117], v[134:137], v[184:187], v[114:117]
	v_mfma_f32_16x16x32_bf16 v[106:109], v[142:145], v[184:187], v[106:109]
	v_mfma_f32_16x16x32_bf16 v[98:101], v[134:137], v[192:195], v[98:101]
	ds_read_b128 v[216:219], v159 offset:3072
	v_mfma_f32_16x16x32_bf16 v[90:93], v[142:145], v[192:195], v[90:93]
	v_mfma_f32_16x16x32_bf16 v[82:85], v[134:137], v[200:203], v[82:85]
	v_mfma_f32_16x16x32_bf16 v[74:77], v[142:145], v[200:203], v[74:77]
	s_setprio 0
	s_barrier
	s_add_i32 s84, 0, 0x1c000
	s_add_i32 s85, s70, s47
	s_mov_b32 m0, s85
	s_nop 0
	global_load_lds_dwordx4 v146, s[96:97]
	s_add_i32 m0, s85, 0x2000
	s_nop 0
	global_load_lds_dwordx4 v148, s[96:97]
	s_waitcnt vmcnt(10)
	s_barrier
	s_waitcnt lgkmcnt(0)
	s_setprio 1
	v_mfma_f32_16x16x32_bf16 v[118:121], v[204:207], v[172:175], v[118:121]
	ds_read_b128 v[224:227], v170 offset:49152
	v_mfma_f32_16x16x32_bf16 v[110:113], v[212:215], v[172:175], v[110:113]
	v_mfma_f32_16x16x32_bf16 v[102:105], v[204:207], v[180:183], v[102:105]
	ds_read_b128 v[228:231], v170 offset:50176
	v_mfma_f32_16x16x32_bf16 v[94:97], v[212:215], v[180:183], v[94:97]
	v_mfma_f32_16x16x32_bf16 v[86:89], v[204:207], v[188:191], v[86:89]
	ds_read_b128 v[232:235], v170 offset:51200
	v_mfma_f32_16x16x32_bf16 v[78:81], v[212:215], v[188:191], v[78:81]
	v_mfma_f32_16x16x32_bf16 v[70:73], v[204:207], v[196:199], v[70:73]
	ds_read_b128 v[236:239], v170 offset:52224
	v_mfma_f32_16x16x32_bf16 v[66:69], v[212:215], v[196:199], v[66:69]
	v_mfma_f32_16x16x32_bf16 v[118:121], v[208:211], v[176:179], v[118:121]
	ds_read_b128 v[240:243], v170 offset:53248
	v_mfma_f32_16x16x32_bf16 v[110:113], v[216:219], v[176:179], v[110:113]
	v_mfma_f32_16x16x32_bf16 v[102:105], v[208:211], v[184:187], v[102:105]
	ds_read_b128 v[244:247], v170 offset:54272
	v_mfma_f32_16x16x32_bf16 v[94:97], v[216:219], v[184:187], v[94:97]
	v_mfma_f32_16x16x32_bf16 v[86:89], v[208:211], v[192:195], v[86:89]
	ds_read_b128 v[248:251], v170 offset:55296
	v_mfma_f32_16x16x32_bf16 v[78:81], v[216:219], v[192:195], v[78:81]
	v_mfma_f32_16x16x32_bf16 v[70:73], v[208:211], v[200:203], v[70:73]
	ds_read_b128 v[220:223], v170 offset:56320
	v_mfma_f32_16x16x32_bf16 v[66:69], v[216:219], v[200:203], v[66:69]
	s_setprio 0
	s_barrier
	s_mov_b32 m0, s57
	s_nop 0
	global_load_lds_dwordx4 v146, s[94:95]
	s_mov_b32 m0, s58
	s_nop 0
	global_load_lds_dwordx4 v148, s[94:95]
	s_waitcnt vmcnt(8)
	s_barrier
	s_waitcnt lgkmcnt(0)
	s_setprio 1
	v_mfma_f32_16x16x32_bf16 v[62:65], v[130:133], v[224:227], v[62:65]
	ds_read_b128 v[172:175], v170
	v_mfma_f32_16x16x32_bf16 v[58:61], v[138:141], v[224:227], v[58:61]
	v_mfma_f32_16x16x32_bf16 v[54:57], v[130:133], v[232:235], v[54:57]
	ds_read_b128 v[176:179], v170 offset:1024
	v_mfma_f32_16x16x32_bf16 v[46:49], v[138:141], v[232:235], v[46:49]
	v_mfma_f32_16x16x32_bf16 v[38:41], v[130:133], v[240:243], v[38:41]
	ds_read_b128 v[180:183], v170 offset:2048
	v_mfma_f32_16x16x32_bf16 v[30:33], v[138:141], v[240:243], v[30:33]
	v_mfma_f32_16x16x32_bf16 v[22:25], v[130:133], v[248:251], v[22:25]
	ds_read_b128 v[184:187], v170 offset:3072
	v_mfma_f32_16x16x32_bf16 v[14:17], v[138:141], v[248:251], v[14:17]
	v_mfma_f32_16x16x32_bf16 v[62:65], v[134:137], v[228:231], v[62:65]
	ds_read_b128 v[188:191], v170 offset:4096
	v_mfma_f32_16x16x32_bf16 v[58:61], v[142:145], v[228:231], v[58:61]
	v_mfma_f32_16x16x32_bf16 v[54:57], v[134:137], v[236:239], v[54:57]
	ds_read_b128 v[192:195], v170 offset:5120
	v_mfma_f32_16x16x32_bf16 v[46:49], v[142:145], v[236:239], v[46:49]
	v_mfma_f32_16x16x32_bf16 v[38:41], v[134:137], v[244:247], v[38:41]
	ds_read_b128 v[196:199], v170 offset:6144
	v_mfma_f32_16x16x32_bf16 v[30:33], v[142:145], v[244:247], v[30:33]
	v_mfma_f32_16x16x32_bf16 v[22:25], v[134:137], v[220:223], v[22:25]
	ds_read_b128 v[200:203], v170 offset:7168
	v_mfma_f32_16x16x32_bf16 v[14:17], v[142:145], v[220:223], v[14:17]
	s_setprio 0
	s_barrier
	s_add_u32 s40, s40, 0x80080
	s_addc_u32 s41, s41, 0
	s_add_i32 s84, s84, s47
	s_mov_b32 m0, s84
	s_nop 0
	global_load_lds_dwordx4 v146, s[40:41]
	s_add_i32 m0, s84, 0x2000
	s_nop 0
	global_load_lds_dwordx4 v148, s[40:41]
	s_waitcnt vmcnt(10)
	s_barrier
	s_waitcnt lgkmcnt(0)
	s_setprio 1
	v_mfma_f32_16x16x32_bf16 v[50:53], v[204:207], v[224:227], v[50:53]
	ds_read_b128 v[130:133], v167
	v_mfma_f32_16x16x32_bf16 v[42:45], v[212:215], v[224:227], v[42:45]
	v_mfma_f32_16x16x32_bf16 v[34:37], v[204:207], v[232:235], v[34:37]
	v_mfma_f32_16x16x32_bf16 v[26:29], v[212:215], v[232:235], v[26:29]
	v_mfma_f32_16x16x32_bf16 v[18:21], v[204:207], v[240:243], v[18:21]
	ds_read_b128 v[134:137], v167 offset:1024
	v_mfma_f32_16x16x32_bf16 v[10:13], v[212:215], v[240:243], v[10:13]
	v_mfma_f32_16x16x32_bf16 v[6:9], v[204:207], v[248:251], v[6:9]
	v_mfma_f32_16x16x32_bf16 v[2:5], v[212:215], v[248:251], v[2:5]
	v_mfma_f32_16x16x32_bf16 v[50:53], v[208:211], v[228:231], v[50:53]
	ds_read_b128 v[138:141], v167 offset:2048
	v_mfma_f32_16x16x32_bf16 v[42:45], v[216:219], v[228:231], v[42:45]
	v_mfma_f32_16x16x32_bf16 v[34:37], v[208:211], v[236:239], v[34:37]
	v_mfma_f32_16x16x32_bf16 v[26:29], v[216:219], v[236:239], v[26:29]
	v_mfma_f32_16x16x32_bf16 v[18:21], v[208:211], v[244:247], v[18:21]
	ds_read_b128 v[142:145], v167 offset:3072
	v_mfma_f32_16x16x32_bf16 v[10:13], v[216:219], v[244:247], v[10:13]
	v_mfma_f32_16x16x32_bf16 v[6:9], v[208:211], v[220:223], v[6:9]
	v_mfma_f32_16x16x32_bf16 v[2:5], v[216:219], v[220:223], v[2:5]
	s_setprio 0
	s_add_i32 s67, s67, 2
	s_add_u32 s38, s38, 0x100
	s_addc_u32 s39, s39, 0
	s_add_u32 s65, s65, 0x100
	s_addc_u32 s66, s66, 0
	s_cmp_gt_u32 s67, 29
	s_barrier
	s_cbranch_scc0 .LBB0_945
	s_branch .Lp6_loop_exit
.LBB0_945:
	s_add_u32 s40, s38, 0xfff80080
	s_addc_u32 s41, s39, -1
	s_cmp_eq_u32 s67, 28
	s_cselect_b32 s43, s29, s41
	s_cselect_b32 s42, s63, s40
	s_cselect_b32 s41, s27, s66
	s_cselect_b32 s40, s64, s65
	s_add_i32 m0, s37, 0xc000
	s_nop 0
	global_load_lds_dwordx4 v150, s[38:39]
	s_add_i32 m0, s37, 0xe000
	s_nop 0
	global_load_lds_dwordx4 v152, s[38:39]
	s_waitcnt vmcnt(10)
	s_barrier
	s_waitcnt lgkmcnt(0)
	s_setprio 1
	v_mfma_f32_16x16x32_bf16 v[126:129], v[130:133], v[172:175], v[126:129]
	ds_read_b128 v[204:207], v171
	v_mfma_f32_16x16x32_bf16 v[122:125], v[138:141], v[172:175], v[122:125]
	v_mfma_f32_16x16x32_bf16 v[114:117], v[130:133], v[180:183], v[114:117]
	v_mfma_f32_16x16x32_bf16 v[106:109], v[138:141], v[180:183], v[106:109]
	v_mfma_f32_16x16x32_bf16 v[98:101], v[130:133], v[188:191], v[98:101]
	ds_read_b128 v[208:211], v171 offset:1024
	v_mfma_f32_16x16x32_bf16 v[90:93], v[138:141], v[188:191], v[90:93]
	v_mfma_f32_16x16x32_bf16 v[82:85], v[130:133], v[196:199], v[82:85]
	v_mfma_f32_16x16x32_bf16 v[74:77], v[138:141], v[196:199], v[74:77]
	v_mfma_f32_16x16x32_bf16 v[126:129], v[134:137], v[176:179], v[126:129]
	ds_read_b128 v[212:215], v171 offset:2048
	v_mfma_f32_16x16x32_bf16 v[122:125], v[142:145], v[176:179], v[122:125]
	v_mfma_f32_16x16x32_bf16 v[114:117], v[134:137], v[184:187], v[114:117]
	v_mfma_f32_16x16x32_bf16 v[106:109], v[142:145], v[184:187], v[106:109]
	v_mfma_f32_16x16x32_bf16 v[98:101], v[134:137], v[192:195], v[98:101]
	ds_read_b128 v[216:219], v171 offset:3072
	v_mfma_f32_16x16x32_bf16 v[90:93], v[142:145], v[192:195], v[90:93]
	v_mfma_f32_16x16x32_bf16 v[82:85], v[134:137], v[200:203], v[82:85]
	v_mfma_f32_16x16x32_bf16 v[74:77], v[142:145], v[200:203], v[74:77]
	s_setprio 0
	s_barrier
	s_add_i32 s68, s59, s47
	s_add_u32 s96, s40, 0x80
	s_addc_u32 s97, s41, 0
	s_mov_b32 m0, s68
	s_nop 0
	global_load_lds_dwordx4 v146, s[40:41]
	s_add_i32 m0, s68, 0x2000
	s_nop 0
	global_load_lds_dwordx4 v148, s[40:41]
	s_waitcnt vmcnt(10)
	s_barrier
	s_waitcnt lgkmcnt(0)
	s_setprio 1
	v_mfma_f32_16x16x32_bf16 v[118:121], v[204:207], v[172:175], v[118:121]
	ds_read_b128 v[224:227], v170 offset:16384
	v_mfma_f32_16x16x32_bf16 v[110:113], v[212:215], v[172:175], v[110:113]
	v_mfma_f32_16x16x32_bf16 v[102:105], v[204:207], v[180:183], v[102:105]
	ds_read_b128 v[228:231], v170 offset:17408
	v_mfma_f32_16x16x32_bf16 v[94:97], v[212:215], v[180:183], v[94:97]
	v_mfma_f32_16x16x32_bf16 v[86:89], v[204:207], v[188:191], v[86:89]
	ds_read_b128 v[232:235], v170 offset:18432
	v_mfma_f32_16x16x32_bf16 v[78:81], v[212:215], v[188:191], v[78:81]
	v_mfma_f32_16x16x32_bf16 v[70:73], v[204:207], v[196:199], v[70:73]
	ds_read_b128 v[236:239], v170 offset:19456
	v_mfma_f32_16x16x32_bf16 v[66:69], v[212:215], v[196:199], v[66:69]
	v_mfma_f32_16x16x32_bf16 v[118:121], v[208:211], v[176:179], v[118:121]
	ds_read_b128 v[240:243], v170 offset:20480
	v_mfma_f32_16x16x32_bf16 v[110:113], v[216:219], v[176:179], v[110:113]
	v_mfma_f32_16x16x32_bf16 v[102:105], v[208:211], v[184:187], v[102:105]
	ds_read_b128 v[244:247], v170 offset:21504
	v_mfma_f32_16x16x32_bf16 v[94:97], v[216:219], v[184:187], v[94:97]
	v_mfma_f32_16x16x32_bf16 v[86:89], v[208:211], v[192:195], v[86:89]
	ds_read_b128 v[248:251], v170 offset:22528
	v_mfma_f32_16x16x32_bf16 v[78:81], v[216:219], v[192:195], v[78:81]
	v_mfma_f32_16x16x32_bf16 v[70:73], v[208:211], v[200:203], v[70:73]
	ds_read_b128 v[220:223], v170 offset:23552
	v_mfma_f32_16x16x32_bf16 v[66:69], v[216:219], v[200:203], v[66:69]
	s_setprio 0
	s_barrier
	s_mov_b32 m0, s37
	s_add_u32 s94, s42, 0x80
	s_addc_u32 s95, s43, 0
	global_load_lds_dwordx4 v146, s[42:43]
	s_mov_b32 m0, s50
	s_nop 0
	global_load_lds_dwordx4 v148, s[42:43]
	s_waitcnt vmcnt(8)
	s_barrier
	s_waitcnt lgkmcnt(0)
	s_setprio 1
	v_mfma_f32_16x16x32_bf16 v[62:65], v[130:133], v[224:227], v[62:65]
	ds_read_b128 v[172:175], v170 offset:32768
	v_mfma_f32_16x16x32_bf16 v[58:61], v[138:141], v[224:227], v[58:61]
	v_mfma_f32_16x16x32_bf16 v[54:57], v[130:133], v[232:235], v[54:57]
	ds_read_b128 v[176:179], v170 offset:33792
	v_mfma_f32_16x16x32_bf16 v[46:49], v[138:141], v[232:235], v[46:49]
	v_mfma_f32_16x16x32_bf16 v[38:41], v[130:133], v[240:243], v[38:41]
	ds_read_b128 v[180:183], v170 offset:34816
	v_mfma_f32_16x16x32_bf16 v[30:33], v[138:141], v[240:243], v[30:33]
	v_mfma_f32_16x16x32_bf16 v[22:25], v[130:133], v[248:251], v[22:25]
	ds_read_b128 v[184:187], v170 offset:35840
	v_mfma_f32_16x16x32_bf16 v[14:17], v[138:141], v[248:251], v[14:17]
	v_mfma_f32_16x16x32_bf16 v[62:65], v[134:137], v[228:231], v[62:65]
	ds_read_b128 v[188:191], v170 offset:36864
	v_mfma_f32_16x16x32_bf16 v[58:61], v[142:145], v[228:231], v[58:61]
	v_mfma_f32_16x16x32_bf16 v[54:57], v[134:137], v[236:239], v[54:57]
	ds_read_b128 v[192:195], v170 offset:37888
	v_mfma_f32_16x16x32_bf16 v[46:49], v[142:145], v[236:239], v[46:49]
	v_mfma_f32_16x16x32_bf16 v[38:41], v[134:137], v[244:247], v[38:41]
	ds_read_b128 v[196:199], v170 offset:38912
	v_mfma_f32_16x16x32_bf16 v[30:33], v[142:145], v[244:247], v[30:33]
	v_mfma_f32_16x16x32_bf16 v[22:25], v[134:137], v[220:223], v[22:25]
	ds_read_b128 v[200:203], v170 offset:39936
	v_mfma_f32_16x16x32_bf16 v[14:17], v[142:145], v[220:223], v[14:17]
	s_setprio 0
	s_barrier
	s_add_u32 s68, s40, 0x80000
	s_addc_u32 s69, s41, 0
	s_add_i32 s70, s60, s47
	s_mov_b32 m0, s70
	s_nop 0
	global_load_lds_dwordx4 v146, s[68:69]
	s_add_i32 m0, s70, 0x2000
	s_nop 0
	global_load_lds_dwordx4 v148, s[68:69]
	s_waitcnt vmcnt(10)
	s_barrier
	s_waitcnt lgkmcnt(0)
	s_setprio 1
	v_mfma_f32_16x16x32_bf16 v[50:53], v[204:207], v[224:227], v[50:53]
	ds_read_b128 v[130:133], v158
	v_mfma_f32_16x16x32_bf16 v[42:45], v[212:215], v[224:227], v[42:45]
	v_mfma_f32_16x16x32_bf16 v[34:37], v[204:207], v[232:235], v[34:37]
	v_mfma_f32_16x16x32_bf16 v[26:29], v[212:215], v[232:235], v[26:29]
	v_mfma_f32_16x16x32_bf16 v[18:21], v[204:207], v[240:243], v[18:21]
	ds_read_b128 v[134:137], v158 offset:1024
	v_mfma_f32_16x16x32_bf16 v[10:13], v[212:215], v[240:243], v[10:13]
	v_mfma_f32_16x16x32_bf16 v[6:9], v[204:207], v[248:251], v[6:9]
	v_mfma_f32_16x16x32_bf16 v[2:5], v[212:215], v[248:251], v[2:5]
	v_mfma_f32_16x16x32_bf16 v[50:53], v[208:211], v[228:231], v[50:53]
	ds_read_b128 v[138:141], v158 offset:2048
	v_mfma_f32_16x16x32_bf16 v[42:45], v[216:219], v[228:231], v[42:45]
	v_mfma_f32_16x16x32_bf16 v[34:37], v[208:211], v[236:239], v[34:37]
	v_mfma_f32_16x16x32_bf16 v[26:29], v[216:219], v[236:239], v[26:29]
	v_mfma_f32_16x16x32_bf16 v[18:21], v[208:211], v[244:247], v[18:21]
	ds_read_b128 v[142:145], v158 offset:3072
	v_mfma_f32_16x16x32_bf16 v[10:13], v[216:219], v[244:247], v[10:13]
	v_mfma_f32_16x16x32_bf16 v[6:9], v[208:211], v[220:223], v[6:9]
	v_mfma_f32_16x16x32_bf16 v[2:5], v[216:219], v[220:223], v[2:5]
	s_setprio 0
	s_barrier
	s_add_i32 s70, 0, 0x18000
	s_add_u32 s42, s42, 0x80000
	s_addc_u32 s43, s43, 0
	s_mov_b32 m0, s51
	s_nop 0
	global_load_lds_dwordx4 v146, s[42:43]
	s_mov_b32 m0, s52
	s_nop 0
	global_load_lds_dwordx4 v148, s[42:43]
	s_waitcnt vmcnt(10)
	s_barrier
	s_waitcnt lgkmcnt(0)
	s_setprio 1
	v_mfma_f32_16x16x32_bf16 v[126:129], v[130:133], v[172:175], v[126:129]
	ds_read_b128 v[204:207], v159
	v_mfma_f32_16x16x32_bf16 v[122:125], v[138:141], v[172:175], v[122:125]
	v_mfma_f32_16x16x32_bf16 v[114:117], v[130:133], v[180:183], v[114:117]
	v_mfma_f32_16x16x32_bf16 v[106:109], v[138:141], v[180:183], v[106:109]
	v_mfma_f32_16x16x32_bf16 v[98:101], v[130:133], v[188:191], v[98:101]
	ds_read_b128 v[208:211], v159 offset:1024
	v_mfma_f32_16x16x32_bf16 v[90:93], v[138:141], v[188:191], v[90:93]
	v_mfma_f32_16x16x32_bf16 v[82:85], v[130:133], v[196:199], v[82:85]
	v_mfma_f32_16x16x32_bf16 v[74:77], v[138:141], v[196:199], v[74:77]
	v_mfma_f32_16x16x32_bf16 v[126:129], v[134:137], v[176:179], v[126:129]
	ds_read_b128 v[212:215], v159 offset:2048
	v_mfma_f32_16x16x32_bf16 v[122:125], v[142:145], v[176:179], v[122:125]
	v_mfma_f32_16x16x32_bf16 v[114:117], v[134:137], v[184:187], v[114:117]
	v_mfma_f32_16x16x32_bf16 v[106:109], v[142:145], v[184:187], v[106:109]
	v_mfma_f32_16x16x32_bf16 v[98:101], v[134:137], v[192:195], v[98:101]
	ds_read_b128 v[216:219], v159 offset:3072
	v_mfma_f32_16x16x32_bf16 v[90:93], v[142:145], v[192:195], v[90:93]
	v_mfma_f32_16x16x32_bf16 v[82:85], v[134:137], v[200:203], v[82:85]
	v_mfma_f32_16x16x32_bf16 v[74:77], v[142:145], v[200:203], v[74:77]
	s_setprio 0
	s_barrier
	s_add_i32 s84, 0, 0x1c000
	s_add_i32 s85, s70, s47
	s_mov_b32 m0, s85
	s_nop 0
	global_load_lds_dwordx4 v146, s[96:97]
	s_add_i32 m0, s85, 0x2000
	s_nop 0
	global_load_lds_dwordx4 v148, s[96:97]
	s_waitcnt vmcnt(10)
	s_barrier
	s_waitcnt lgkmcnt(0)
	s_setprio 1
	v_mfma_f32_16x16x32_bf16 v[118:121], v[204:207], v[172:175], v[118:121]
	ds_read_b128 v[224:227], v170 offset:49152
	v_mfma_f32_16x16x32_bf16 v[110:113], v[212:215], v[172:175], v[110:113]
	v_mfma_f32_16x16x32_bf16 v[102:105], v[204:207], v[180:183], v[102:105]
	ds_read_b128 v[228:231], v170 offset:50176
	v_mfma_f32_16x16x32_bf16 v[94:97], v[212:215], v[180:183], v[94:97]
	v_mfma_f32_16x16x32_bf16 v[86:89], v[204:207], v[188:191], v[86:89]
	ds_read_b128 v[232:235], v170 offset:51200
	v_mfma_f32_16x16x32_bf16 v[78:81], v[212:215], v[188:191], v[78:81]
	v_mfma_f32_16x16x32_bf16 v[70:73], v[204:207], v[196:199], v[70:73]
	ds_read_b128 v[236:239], v170 offset:52224
	v_mfma_f32_16x16x32_bf16 v[66:69], v[212:215], v[196:199], v[66:69]
	v_mfma_f32_16x16x32_bf16 v[118:121], v[208:211], v[176:179], v[118:121]
	ds_read_b128 v[240:243], v170 offset:53248
	v_mfma_f32_16x16x32_bf16 v[110:113], v[216:219], v[176:179], v[110:113]
	v_mfma_f32_16x16x32_bf16 v[102:105], v[208:211], v[184:187], v[102:105]
	ds_read_b128 v[244:247], v170 offset:54272
	v_mfma_f32_16x16x32_bf16 v[94:97], v[216:219], v[184:187], v[94:97]
	v_mfma_f32_16x16x32_bf16 v[86:89], v[208:211], v[192:195], v[86:89]
	ds_read_b128 v[248:251], v170 offset:55296
	v_mfma_f32_16x16x32_bf16 v[78:81], v[216:219], v[192:195], v[78:81]
	v_mfma_f32_16x16x32_bf16 v[70:73], v[208:211], v[200:203], v[70:73]
	ds_read_b128 v[220:223], v170 offset:56320
	v_mfma_f32_16x16x32_bf16 v[66:69], v[216:219], v[200:203], v[66:69]
	s_setprio 0
	s_barrier
	s_mov_b32 m0, s57
	s_nop 0
	global_load_lds_dwordx4 v146, s[94:95]
	s_mov_b32 m0, s58
	s_nop 0
	global_load_lds_dwordx4 v148, s[94:95]
	s_waitcnt vmcnt(8)
	s_barrier
	s_waitcnt lgkmcnt(0)
	s_setprio 1
	v_mfma_f32_16x16x32_bf16 v[62:65], v[130:133], v[224:227], v[62:65]
	ds_read_b128 v[172:175], v170
	v_mfma_f32_16x16x32_bf16 v[58:61], v[138:141], v[224:227], v[58:61]
	v_mfma_f32_16x16x32_bf16 v[54:57], v[130:133], v[232:235], v[54:57]
	ds_read_b128 v[176:179], v170 offset:1024
	v_mfma_f32_16x16x32_bf16 v[46:49], v[138:141], v[232:235], v[46:49]
	v_mfma_f32_16x16x32_bf16 v[38:41], v[130:133], v[240:243], v[38:41]
	ds_read_b128 v[180:183], v170 offset:2048
	v_mfma_f32_16x16x32_bf16 v[30:33], v[138:141], v[240:243], v[30:33]
	v_mfma_f32_16x16x32_bf16 v[22:25], v[130:133], v[248:251], v[22:25]
	ds_read_b128 v[184:187], v170 offset:3072
	v_mfma_f32_16x16x32_bf16 v[14:17], v[138:141], v[248:251], v[14:17]
	v_mfma_f32_16x16x32_bf16 v[62:65], v[134:137], v[228:231], v[62:65]
	ds_read_b128 v[188:191], v170 offset:4096
	v_mfma_f32_16x16x32_bf16 v[58:61], v[142:145], v[228:231], v[58:61]
	v_mfma_f32_16x16x32_bf16 v[54:57], v[134:137], v[236:239], v[54:57]
	ds_read_b128 v[192:195], v170 offset:5120
	v_mfma_f32_16x16x32_bf16 v[46:49], v[142:145], v[236:239], v[46:49]
	v_mfma_f32_16x16x32_bf16 v[38:41], v[134:137], v[244:247], v[38:41]
	ds_read_b128 v[196:199], v170 offset:6144
	v_mfma_f32_16x16x32_bf16 v[30:33], v[142:145], v[244:247], v[30:33]
	v_mfma_f32_16x16x32_bf16 v[22:25], v[134:137], v[220:223], v[22:25]
	ds_read_b128 v[200:203], v170 offset:7168
	v_mfma_f32_16x16x32_bf16 v[14:17], v[142:145], v[220:223], v[14:17]
	s_setprio 0
	s_barrier
	s_add_u32 s40, s40, 0x80080
	s_addc_u32 s41, s41, 0
	s_add_i32 s84, s84, s47
	s_mov_b32 m0, s84
	s_nop 0
	global_load_lds_dwordx4 v146, s[40:41]
	s_add_i32 m0, s84, 0x2000
	s_nop 0
	global_load_lds_dwordx4 v148, s[40:41]
	s_waitcnt vmcnt(10)
	s_barrier
	s_waitcnt lgkmcnt(0)
	s_setprio 1
	v_mfma_f32_16x16x32_bf16 v[50:53], v[204:207], v[224:227], v[50:53]
	ds_read_b128 v[130:133], v167
	v_mfma_f32_16x16x32_bf16 v[42:45], v[212:215], v[224:227], v[42:45]
	v_mfma_f32_16x16x32_bf16 v[34:37], v[204:207], v[232:235], v[34:37]
	v_mfma_f32_16x16x32_bf16 v[26:29], v[212:215], v[232:235], v[26:29]
	v_mfma_f32_16x16x32_bf16 v[18:21], v[204:207], v[240:243], v[18:21]
	ds_read_b128 v[134:137], v167 offset:1024
	v_mfma_f32_16x16x32_bf16 v[10:13], v[212:215], v[240:243], v[10:13]
	v_mfma_f32_16x16x32_bf16 v[6:9], v[204:207], v[248:251], v[6:9]
	v_mfma_f32_16x16x32_bf16 v[2:5], v[212:215], v[248:251], v[2:5]
	v_mfma_f32_16x16x32_bf16 v[50:53], v[208:211], v[228:231], v[50:53]
	ds_read_b128 v[138:141], v167 offset:2048
	v_mfma_f32_16x16x32_bf16 v[42:45], v[216:219], v[228:231], v[42:45]
	v_mfma_f32_16x16x32_bf16 v[34:37], v[208:211], v[236:239], v[34:37]
	v_mfma_f32_16x16x32_bf16 v[26:29], v[216:219], v[236:239], v[26:29]
	v_mfma_f32_16x16x32_bf16 v[18:21], v[208:211], v[244:247], v[18:21]
	ds_read_b128 v[142:145], v167 offset:3072
	v_mfma_f32_16x16x32_bf16 v[10:13], v[216:219], v[244:247], v[10:13]
	v_mfma_f32_16x16x32_bf16 v[6:9], v[208:211], v[220:223], v[6:9]
	v_mfma_f32_16x16x32_bf16 v[2:5], v[216:219], v[220:223], v[2:5]
	s_setprio 0
	s_add_i32 s67, s67, 2
	s_add_u32 s38, s38, 0x100
	s_addc_u32 s39, s39, 0
	s_add_u32 s65, s65, 0x100
	s_addc_u32 s66, s66, 0
	s_cmp_gt_u32 s67, 29
	s_barrier
	s_cbranch_scc0 .LBB0_945
